# UKV GEMM: waves 0-3 take the stagger-rebalancing barrier before the last tile's epilogue (both wave halves run EpiKV concurrently)
# speedup vs baseline: 1.0057x; 1.0057x over previous
; #define LAS __attribute__((address_space(3)))
; __device__ __forceinline__ CArgs get_args() { CArgs p = (CArgs)__builtin_amdgcn_kernarg_segment_ptr(); asm volatile("" : "+s"(p)); return p; }
; __device__ __forceinline__ unsigned xb_add(unsigned* p, unsigned v) { return __hip_atomic_fetch_add(p, v, __ATOMIC_RELAXED, __HIP_MEMORY_SCOPE_AGENT); }
; __device__ __forceinline__ unsigned xb_xcc_id() { return (unsigned)__builtin_amdgcn_s_getreg((3 << 11) | 20) & 0xFu; }
; __device__ __forceinline__ XcdBarrier xcd_barrier_post(unsigned* bar, volatile LAS unsigned* st) {
;     XcdBarrier b; b.bar = bar; b.x = xb_xcc_id(); b.st = st;
;     if (threadIdx.x == 0) (void)xb_add(&bar[XB_XCNT(b.x)], 1u);
;     return b;
; __global__ void __launch_bounds__(NTHR, 2) mk_fwd(Args a_by_value) {
;     ...
;     unsigned char* ws; { CArgs a0 = get_args(); ws = a0->ws; }
;     const int ph_lo = get_args()->ph_lo, ph_hi = get_args()->ph_hi;
;     float* rowss = (float*)(ws + WS_CTL + CTL_ROWSS);
;     bf16_t* U = (bf16_t*)(ws + WS_U); bf16_t* Hb = U; bf16_t* XB = (bf16_t*)(ws + WS_XB); bf16_t* Y = (bf16_t*)(ws + WS_Y);
;     unsigned char* wsw = ws + WS_W;
;     volatile LAS unsigned* xst = (volatile LAS unsigned*)(lds + LDS_BYTES - 16);
;     if (threadIdx.x < 4) xst[threadIdx.x] = 0u;
;     __syncthreads();
;     XcdBarrier xbar; xbar.bar = (unsigned*)(ws + WS_BAR); xbar.x = 0; xbar.st = xst;
;     if (USE_XCD_BAR && ph_hi - ph_lo > 1) xbar = xcd_barrier_post((unsigned*)(ws + WS_BAR), xst);
_Z6mk_fwd4Args:
	s_load_dwordx2 s[64:65], s[0:1], 0xf8
	v_writelane_b32 v253, s2, 0
	s_mov_b64 s[2:3], s[0:1]
	s_load_dwordx2 s[66:67], s[2:3], 0xe8
	s_mov_b64 s[2:3], s[0:1]
	s_load_dword s2, s[2:3], 0xf0
	v_and_b32_e32 v244, 0x3ff, v0
	v_cmp_gt_u32_e32 vcc, 4, v244
	s_waitcnt lgkmcnt(0)
	v_writelane_b32 v253, s2, 1
	s_mov_b64 s[2:3], s[0:1]
	s_load_dword s2, s[2:3], 0xf4
	s_waitcnt lgkmcnt(0)
	v_writelane_b32 v253, s2, 2
	s_add_u32 s2, s0, 0xf8
	v_writelane_b32 v253, s0, 3
	s_addc_u32 s3, s1, 0
	s_nop 0
	v_writelane_b32 v253, s1, 4
	v_writelane_b32 v253, s2, 5
	s_nop 1
	v_writelane_b32 v253, s3, 6
	s_and_saveexec_b64 s[0:1], vcc
	v_lshl_add_u32 v1, v244, 2, 0
	v_add_u32_e32 v1, 0x23ff0, v1
	v_mov_b32_e32 v2, 0
	ds_write_b32 v1, v2
	s_or_b64 exec, exec, s[0:1]
	s_add_u32 s0, s66, 0x180000
	v_readlane_b32 s2, v253, 1
	v_readlane_b32 s3, v253, 2
	s_addc_u32 s1, s67, 0
	s_sub_i32 s2, s3, s2
	s_mov_b32 s6, 0
	s_nop 3
	v_writelane_b32 v255, s6, 43
	s_nop 3
	s_cmp_lt_i32 s2, 2
	v_cmp_eq_u32_e32 vcc, 0, v244
	s_waitcnt lgkmcnt(0)
	s_barrier
	s_cbranch_scc1 .LBB0_7
	s_getreg_b32 s2, hwreg(HW_REG_XCC_ID, 0, 4)
	s_and_b32 s6, s2, 15
	s_and_saveexec_b64 s[2:3], vcc
	s_cbranch_execz .LBB0_6
	s_mov_b64 s[4:5], exec
	v_mbcnt_lo_u32_b32 v1, s4, 0
	v_mbcnt_hi_u32_b32 v1, s5, v1
	v_cmp_eq_u32_e32 vcc, 0, v1
	s_and_b64 s[8:9], exec, vcc
	s_mov_b64 exec, s[8:9]
	s_cbranch_execz .LBB0_6
	s_lshl_b32 s7, s6, 8
	s_bcnt1_i32_b64 s4, s[4:5]
	v_mov_b32_e32 v1, s7
	v_mov_b32_e32 v2, s4
	global_atomic_add v1, v2, s[0:1] offset:1024

; #define PG8_WAIT_V(n) asm volatile("s_waitcnt vmcnt(" #n ")" ::: "memory")
; #define PG8_BAR __builtin_amdgcn_s_barrier()
; template <class Epi, class Sched, bool ALIGN_EPI>
; __device__ __forceinline__ void gemm_phase(PG8_LAS unsigned char* lds, const Gemm g, const Sched& S, const Epi& E) {
;     ...
;         if constexpr (ALIGN_EPI) { if (wr == 0) PG8_BAR; }
;         E(acc, cur, wr, wc, fr, fq);
;     ...
;     PG8_WAIT_V(0);
;     if constexpr (!ALIGN_EPI) { if (wr == 0) PG8_BAR; }
;     PG8_BAR;
.LBB0_133:
	s_and_b64 s[98:99], exec, s[42:43]
	s_cbranch_scc0 .Lea_s2
	v_readlane_b32 s98, v255, 16
	s_nop 0
	s_cmpk_gt_u32 s98, 0xff
	s_cbranch_scc1 .Lea_s2
	s_barrier
	s_mov_b32 s98, 1
	s_nop 0
	v_writelane_b32 v255, s98, 43

; #define PG8_WAIT_V(n) asm volatile("s_waitcnt vmcnt(" #n ")" ::: "memory")
; #define PG8_BAR __builtin_amdgcn_s_barrier()
; template <class Epi, class Sched, bool ALIGN_EPI>
; __device__ __forceinline__ void gemm_phase(PG8_LAS unsigned char* lds, const Gemm g, const Sched& S, const Epi& E) {
;     ...
;     PG8_WAIT_V(0);
;     if constexpr (!ALIGN_EPI) { if (wr == 0) PG8_BAR; }
;     PG8_BAR;
.LBB0_165:
	s_waitcnt vmcnt(0)
	v_readlane_b32 s2, v255, 16
	s_cmpk_gt_u32 s2, 0xff
	s_cbranch_scc1 .LBB0_167
	v_readlane_b32 s98, v255, 43
	s_mov_b32 s99, 0
	s_nop 1
	v_writelane_b32 v255, s99, 43
	s_cmp_eq_u32 s98, 1
	s_cbranch_scc1 .LBB0_167
	s_barrier
